# idle workgroups of the layer-0 out-proj phase touch the layer-0 MLP weight copies (16 MiB) so the following up/down GEMM phases read them from the memory-side cache
# speedup vs baseline: 1.0109x; 1.0109x over previous
.Lpf4:
	s_cmp_lt_u32 s2, 0xc0
	s_cbranch_scc1 .Lpf4_done
	v_mbcnt_lo_u32_b32 v240, -1, 0
	v_mbcnt_hi_u32_b32 v240, -1, v240
	s_sub_i32 s98, s2, 0xc0
	s_lshl_b32 s98, s98, 3
	s_add_i32 s98, s98, s94
	v_lshl_add_u32 v240, s98, 6, v240
	v_lshlrev_b32_e32 v240, 4, v240
	s_add_u32 s98, s54, 0xb00000
	s_addc_u32 s99, s55, 0
	global_load_dword v241, v240, s[98:99]
	s_add_u32 s98, s98, 0x80000
	s_addc_u32 s99, s99, 0
	global_load_dword v241, v240, s[98:99]
	s_add_u32 s98, s98, 0x80000
	s_addc_u32 s99, s99, 0
	global_load_dword v241, v240, s[98:99]
	s_add_u32 s98, s98, 0x80000
	s_addc_u32 s99, s99, 0
	global_load_dword v241, v240, s[98:99]
	s_add_u32 s98, s98, 0x80000
	s_addc_u32 s99, s99, 0
	global_load_dword v241, v240, s[98:99]
	s_add_u32 s98, s98, 0x80000
	s_addc_u32 s99, s99, 0
	global_load_dword v241, v240, s[98:99]
	s_add_u32 s98, s98, 0x80000
	s_addc_u32 s99, s99, 0
	global_load_dword v241, v240, s[98:99]
	s_add_u32 s98, s98, 0x80000
	s_addc_u32 s99, s99, 0
	global_load_dword v241, v240, s[98:99]
	s_add_u32 s98, s98, 0x80000
	s_addc_u32 s99, s99, 0
	global_load_dword v241, v240, s[98:99]
	s_add_u32 s98, s98, 0x80000
	s_addc_u32 s99, s99, 0
	global_load_dword v241, v240, s[98:99]
	s_add_u32 s98, s98, 0x80000
	s_addc_u32 s99, s99, 0
	global_load_dword v241, v240, s[98:99]
	s_add_u32 s98, s98, 0x80000
	s_addc_u32 s99, s99, 0
	global_load_dword v241, v240, s[98:99]
	s_add_u32 s98, s98, 0x80000
	s_addc_u32 s99, s99, 0
	global_load_dword v241, v240, s[98:99]
	s_add_u32 s98, s98, 0x80000
	s_addc_u32 s99, s99, 0
	global_load_dword v241, v240, s[98:99]
	s_add_u32 s98, s98, 0x80000
	s_addc_u32 s99, s99, 0
	global_load_dword v241, v240, s[98:99]
	s_add_u32 s98, s98, 0x80000
	s_addc_u32 s99, s99, 0
	global_load_dword v241, v240, s[98:99]
	s_add_u32 s98, s98, 0x80000
	s_addc_u32 s99, s99, 0
	global_load_dword v241, v240, s[98:99]
	s_add_u32 s98, s98, 0x80000
	s_addc_u32 s99, s99, 0
	global_load_dword v241, v240, s[98:99]
	s_add_u32 s98, s98, 0x80000
	s_addc_u32 s99, s99, 0
	global_load_dword v241, v240, s[98:99]
	s_add_u32 s98, s98, 0x80000
	s_addc_u32 s99, s99, 0
	global_load_dword v241, v240, s[98:99]
	s_add_u32 s98, s98, 0x80000
	s_addc_u32 s99, s99, 0
	global_load_dword v241, v240, s[98:99]
	s_add_u32 s98, s98, 0x80000
	s_addc_u32 s99, s99, 0
	global_load_dword v241, v240, s[98:99]
	s_add_u32 s98, s98, 0x80000
	s_addc_u32 s99, s99, 0
	global_load_dword v241, v240, s[98:99]
	s_add_u32 s98, s98, 0x80000
	s_addc_u32 s99, s99, 0
	global_load_dword v241, v240, s[98:99]
	s_add_u32 s98, s98, 0x80000
	s_addc_u32 s99, s99, 0
	global_load_dword v241, v240, s[98:99]
	s_add_u32 s98, s98, 0x80000
	s_addc_u32 s99, s99, 0
	global_load_dword v241, v240, s[98:99]
	s_add_u32 s98, s98, 0x80000
	s_addc_u32 s99, s99, 0
	global_load_dword v241, v240, s[98:99]
	s_add_u32 s98, s98, 0x80000
	s_addc_u32 s99, s99, 0
	global_load_dword v241, v240, s[98:99]
	s_add_u32 s98, s98, 0x80000
	s_addc_u32 s99, s99, 0
	global_load_dword v241, v240, s[98:99]
	s_add_u32 s98, s98, 0x80000
	s_addc_u32 s99, s99, 0
	global_load_dword v241, v240, s[98:99]
	s_add_u32 s98, s98, 0x80000
	s_addc_u32 s99, s99, 0
	global_load_dword v241, v240, s[98:99]
	s_add_u32 s98, s98, 0x80000
	s_addc_u32 s99, s99, 0
	global_load_dword v241, v240, s[98:99]
	s_add_u32 s98, s98, 0x80000
	s_addc_u32 s99, s99, 0
	s_waitcnt vmcnt(0)
.Lpf4_done:
.LBB0_378:
	s_cmp_gt_i32 s41, 6
	s_cselect_b64 s[4:5], -1, 0
	s_and_b64 s[0:1], s[4:5], s[12:13]
	s_andn2_b64 vcc, exec, s[0:1]
	s_cbranch_vccnz .LBB0_428
	s_waitcnt vmcnt(0)
	s_waitcnt vmcnt(0)
	s_barrier
	s_mov_b64 s[0:1], exec
	v_readlane_b32 s6, v246, 0
	v_readlane_b32 s7, v246, 1
	s_and_b64 s[6:7], s[0:1], s[6:7]
	s_mov_b64 exec, s[6:7]
	s_cbranch_execz .LBB0_427
	s_add_i32 s3, 0, 0x20000
	v_mov_b32_e32 v0, s3
	s_waitcnt vmcnt(0) expcnt(0) lgkmcnt(0)
	ds_read_b32 v2, v0
	s_add_i32 s3, 0, 0x20004
	v_mov_b32_e32 v0, s3
	ds_read_b32 v0, v0
	s_waitcnt lgkmcnt(1)
	v_cmp_ne_u32_e32 vcc, 0, v2
	s_cbranch_vccnz .LBB0_395
	s_add_u32 s6, s54, 0xd600200
	s_addc_u32 s7, s55, 0
	s_add_u32 s8, s54, 0xd600400
	s_addc_u32 s9, s55, 0
	s_add_u32 s10, s54, 0xd600500
	s_addc_u32 s11, s55, 0
	s_add_u32 s12, s54, 0xd600600
	s_addc_u32 s13, s55, 0
	s_add_u32 s14, s54, 0xd600700
	s_addc_u32 s15, s55, 0
	s_add_u32 s16, s54, 0xd600800
	s_addc_u32 s17, s55, 0
	s_add_u32 s18, s54, 0xd600900
	s_addc_u32 s19, s55, 0
	s_add_u32 s20, s54, 0xd600a00
	s_addc_u32 s21, s55, 0
	s_add_u32 s22, s54, 0xd600b00
	s_addc_u32 s23, s55, 0
	s_add_u32 s26, s54, 0xd600c00
	s_addc_u32 s27, s55, 0
	s_add_u32 s28, s54, 0xd600d00
	s_addc_u32 s29, s55, 0
	s_add_u32 s30, s54, 0xd600e00
	s_addc_u32 s31, s55, 0
	s_add_u32 s34, s54, 0xd600f00
	s_addc_u32 s35, s55, 0
	s_add_u32 s36, s54, 0xd601000
	s_addc_u32 s37, s55, 0
	s_add_u32 s38, s54, 0xd601100
	s_addc_u32 s39, s55, 0
	s_add_u32 s64, s54, 0xd601200
	v_readlane_b32 s3, v246, 2
	s_addc_u32 s65, s55, 0
	s_mul_i32 s3, s57, s3
	s_add_u32 s66, s54, 0xd601300
	s_mul_i32 s3, s3, s56
	s_addc_u32 s67, s55, 0
	s_mov_b32 s24, 1
	v_mov_b32_e32 v16, 0
	s_branch .LBB0_383
